# v24 + XCD-hierarchical grid barrier (13 sites): per-XCC arrival counters, one L2 write-back per XCD, 8-way top counter; counters in unused ws rows zeroed in phase 0
# speedup vs baseline: 1.0358x; 1.0358x over previous
; DI void phase_prep(const Params& p, unsigned char* lds) {
;     ...
;     if (blockIdx.x == 0 && threadIdx.x < 64) { ((unsigned*)(ws + WS_BND))[threadIdx.x] = 0u; ((unsigned*)(ws + WS_BAR))[threadIdx.x] = 0u; }
.LBB0_146:
	s_or_b64 exec, exec, s[34:35]
	s_cmp_eq_u32 s33, 0
	s_cselect_b64 s[0:1], -1, 0
	v_cmp_gt_u32_e32 vcc, 64, v1
	s_and_b64 s[0:1], s[0:1], vcc
	s_and_saveexec_b64 s[2:3], s[0:1]
	s_cbranch_execz .LBB0_148
	v_lshlrev_b32_e32 v2, 2, v1
	s_waitcnt lgkmcnt(0)
	v_mov_b32_e32 v3, 0
	v_lshl_add_u64 v[4:5], s[42:43], 0, v[2:3]
	v_add_co_u32_e32 v4, vcc, 0x1fa20000, v4
	s_nop 1
	v_addc_co_u32_e32 v5, vcc, 0, v5, vcc
	global_store_dword v[4:5], v3, off
	global_store_dword v2, v3, s[62:63]
	v_lshlrev_b32_e32 v12, 4, v1
	v_add_u32_e32 v13, 0x1000, v12
	v_mov_b32_e32 v8, 0
	v_mov_b32_e32 v9, 0
	v_mov_b32_e32 v10, 0
	v_mov_b32_e32 v11, 0
	s_add_u32 s0, s42, 0x600000
	s_addc_u32 s1, s43, 0
	global_store_dwordx4 v12, v[8:11], s[0:1]
	global_store_dwordx4 v12, v[8:11], s[0:1] offset:1024
	global_store_dwordx4 v12, v[8:11], s[0:1] offset:2048
	global_store_dwordx4 v12, v[8:11], s[0:1] offset:3072
	global_store_dwordx4 v13, v[8:11], s[0:1]

; #define SYNC(k) if (p.ph_lo <= (k) && (k) + 1 < p.ph_hi) { if ((k) == 0) grid.sync(); else gbar(bctr, bgen, gridDim.x); }
; DI void gbar(unsigned* ctr, unsigned& gen, unsigned G) {
;     asm volatile("s_waitcnt vmcnt(0)" ::: "memory");
;     __syncthreads();
;     gen += 1;
;     if (threadIdx.x == 0) {
;         __builtin_amdgcn_fence(__ATOMIC_RELEASE, "agent");
;         asm volatile("s_waitcnt vmcnt(0)" ::: "memory");
;         __hip_atomic_fetch_add(ctr, 1u, __ATOMIC_RELAXED, __HIP_MEMORY_SCOPE_AGENT);
;         while (__hip_atomic_load(ctr, __ATOMIC_RELAXED, __HIP_MEMORY_SCOPE_AGENT) < gen * G) __builtin_amdgcn_s_sleep(32);
;         __builtin_amdgcn_fence(__ATOMIC_ACQUIRE, "agent");
;         asm volatile("s_waitcnt vmcnt(0)" ::: "memory");
;     }
;     __syncthreads();
; }
; __global__ void __launch_bounds__(NTHREADS) fwd_megakernel(Params p) {
;     ...
;     SYNC(1)
.LBB0_1197:
	s_or_b64 exec, exec, s[18:19]
	v_cmp_gt_i32_e32 vcc, 2, v1
	v_cmp_lt_i32_e64 s[2:3], 2, v2
	s_and_b64 s[0:1], vcc, s[2:3]
	v_mov_b32_e32 v210, 0
	s_and_saveexec_b64 s[2:3], s[0:1]
	s_cbranch_execz .LBB0_1205
	s_waitcnt vmcnt(0)
	s_waitcnt lgkmcnt(0)
	v_and_b32_e32 v3, 0x3ff, v0
	v_cmp_eq_u32_e32 vcc, 0, v3
	s_waitcnt vmcnt(0)
	s_barrier
	s_and_saveexec_b64 s[4:5], vcc
	s_cbranch_execz .LBB0_1204
	s_getreg_b32 s1, hwreg(HW_REG_XCC_ID, 0, 4)
	s_lshl_b32 s1, s1, 8
	s_add_u32 s12, s42, 0x600000
	s_addc_u32 s13, s43, 0
	s_add_u32 s12, s12, s1
	s_addc_u32 s13, s13, 0
	s_add_u32 s14, s42, 0x601000
	s_addc_u32 s15, s43, 0
	s_lshr_b32 s16, s86, 3
	v_mov_b32_e32 v2, 0
	v_mov_b32_e32 v3, 1
	v_mov_b32_e32 v7, 1
	global_atomic_add v4, v2, v3, s[12:13] sc0
	v_mul_lo_u32 v8, v7, s16
	s_mov_b32 s0, 0
	s_waitcnt vmcnt(0)
	v_add_u32_e32 v4, 1, v4
	v_cmp_eq_u32_e32 vcc, v4, v8
	s_cbranch_vccz .Lxb_nl_0
	buffer_wbl2 sc1
	s_waitcnt vmcnt(0)
	global_atomic_add v4, v2, v3, s[14:15] sc0
	v_lshlrev_b32_e32 v8, 3, v7
	s_waitcnt vmcnt(0)
	v_add_u32_e32 v4, 1, v4
	v_cmp_eq_u32_e32 vcc, v4, v8
	s_cbranch_vccz .Lxb_wt_0
	global_atomic_add v2, v3, s[14:15] offset:256
	s_branch .Lxb_lr_0
.Lxb_wt_0:
	s_sleep 1
	global_load_dword v4, v2, s[14:15] offset:256 sc1
	s_add_u32 s0, s0, 1
	s_waitcnt vmcnt(0)
	v_cmp_ge_u32_e32 vcc, v4, v7
	s_cbranch_vccnz .Lxb_lr_0
	s_cmp_lt_u32 s0, 0x20000
	s_cbranch_scc1 .Lxb_wt_0
.Lxb_lr_0:
	buffer_inv sc1
	global_atomic_add v2, v3, s[12:13] offset:128
	s_waitcnt vmcnt(0)
	s_branch .Lxb_dn_0
.Lxb_nl_0:
	s_sleep 1
	global_load_dword v4, v2, s[12:13] offset:128 sc1
	s_add_u32 s0, s0, 1
	s_waitcnt vmcnt(0)
	v_cmp_ge_u32_e32 vcc, v4, v7
	s_cbranch_vccnz .Lxb_na_0
	s_cmp_lt_u32 s0, 0x20000
	s_cbranch_scc1 .Lxb_nl_0

; #define SYNC(k) if (p.ph_lo <= (k) && (k) + 1 < p.ph_hi) { if ((k) == 0) grid.sync(); else gbar(bctr, bgen, gridDim.x); }
; DI void gbar(unsigned* ctr, unsigned& gen, unsigned G) {
;     ...
;         asm volatile("s_waitcnt vmcnt(0)" ::: "memory");
;     }
;     __syncthreads();
; __global__ void __launch_bounds__(NTHREADS) fwd_megakernel(Params p) {
;     ...
;     SYNC(1)
.Lxb_dn_0:
	v_mov_b32_e32 v1, s90
	v_mov_b32_e32 v2, s91

; #define SYNC(k) if (p.ph_lo <= (k) && (k) + 1 < p.ph_hi) { if ((k) == 0) grid.sync(); else gbar(bctr, bgen, gridDim.x); }
; DI void gbar(unsigned* ctr, unsigned& gen, unsigned G) {
;     asm volatile("s_waitcnt vmcnt(0)" ::: "memory");
;     __syncthreads();
;     gen += 1;
;     if (threadIdx.x == 0) {
;         __builtin_amdgcn_fence(__ATOMIC_RELEASE, "agent");
;         asm volatile("s_waitcnt vmcnt(0)" ::: "memory");
;         __hip_atomic_fetch_add(ctr, 1u, __ATOMIC_RELAXED, __HIP_MEMORY_SCOPE_AGENT);
;         while (__hip_atomic_load(ctr, __ATOMIC_RELAXED, __HIP_MEMORY_SCOPE_AGENT) < gen * G) __builtin_amdgcn_s_sleep(32);
;         __builtin_amdgcn_fence(__ATOMIC_ACQUIRE, "agent");
;         asm volatile("s_waitcnt vmcnt(0)" ::: "memory");
;     }
;     __syncthreads();
; }
; __global__ void __launch_bounds__(NTHREADS) fwd_megakernel(Params p) {
;     ...
;     SYNC(2)
.LBB0_1236:
	s_or_b64 exec, exec, s[22:23]
	s_cmp_lt_i32 s90, 3
	s_cselect_b64 s[0:1], -1, 0
	s_cmp_gt_i32 s91, 3
	s_cselect_b64 s[2:3], -1, 0
	s_and_b64 s[0:1], s[0:1], s[2:3]
	s_andn2_b64 vcc, exec, s[0:1]
	s_cbranch_vccnz .LBB0_1245
	s_waitcnt vmcnt(0)
	v_and_b32_e32 v1, 0x3ff, v0
	v_add_u32_e32 v210, 1, v210
	v_cmp_eq_u32_e32 vcc, 0, v1
	v_mov_b32_e32 v1, s90
	s_waitcnt lgkmcnt(0)
	v_mov_b32_e32 v5, s91
	s_waitcnt vmcnt(0)
	s_barrier
	s_and_saveexec_b64 s[2:3], vcc
	s_cbranch_execz .LBB0_1244
	s_getreg_b32 s1, hwreg(HW_REG_XCC_ID, 0, 4)
	s_lshl_b32 s1, s1, 8
	s_add_u32 s12, s42, 0x600000
	s_addc_u32 s13, s43, 0
	s_add_u32 s12, s12, s1
	s_addc_u32 s13, s13, 0
	s_add_u32 s14, s42, 0x601000
	s_addc_u32 s15, s43, 0
	s_lshr_b32 s16, s86, 3
	v_mov_b32_e32 v2, 0
	v_mov_b32_e32 v3, 1
	v_mov_b32_e32 v7, v210
	global_atomic_add v4, v2, v3, s[12:13] sc0
	v_mul_lo_u32 v8, v7, s16
	s_mov_b32 s0, 0
	s_waitcnt vmcnt(0)
	v_add_u32_e32 v4, 1, v4
	v_cmp_eq_u32_e32 vcc, v4, v8
	s_cbranch_vccz .Lxb_nl_1
	buffer_wbl2 sc1
	s_waitcnt vmcnt(0)
	global_atomic_add v4, v2, v3, s[14:15] sc0
	v_lshlrev_b32_e32 v8, 3, v7
	s_waitcnt vmcnt(0)
	v_add_u32_e32 v4, 1, v4
	v_cmp_eq_u32_e32 vcc, v4, v8
	s_cbranch_vccz .Lxb_wt_1
	global_atomic_add v2, v3, s[14:15] offset:256
	s_branch .Lxb_lr_1

; #define SYNC(k) if (p.ph_lo <= (k) && (k) + 1 < p.ph_hi) { if ((k) == 0) grid.sync(); else gbar(bctr, bgen, gridDim.x); }
; DI void gbar(unsigned* ctr, unsigned& gen, unsigned G) {
;     ...
;         asm volatile("s_waitcnt vmcnt(0)" ::: "memory");
;     }
;     __syncthreads();
; __global__ void __launch_bounds__(NTHREADS) fwd_megakernel(Params p) {
;     ...
;     SYNC(2)
.Lxb_na_1:
	buffer_inv sc1
	s_waitcnt vmcnt(0)
.Lxb_dn_1:
	v_mov_b32_e32 v1, s90
	v_mov_b32_e32 v5, s91
.LBB0_1244:
	s_or_b64 exec, exec, s[2:3]
	s_barrier
	s_branch .LBB0_1246

; #define SYNC(k) if (p.ph_lo <= (k) && (k) + 1 < p.ph_hi) { if ((k) == 0) grid.sync(); else gbar(bctr, bgen, gridDim.x); }
; DI void gbar(unsigned* ctr, unsigned& gen, unsigned G) {
;     asm volatile("s_waitcnt vmcnt(0)" ::: "memory");
;     __syncthreads();
;     gen += 1;
;     if (threadIdx.x == 0) {
;         __builtin_amdgcn_fence(__ATOMIC_RELEASE, "agent");
;         asm volatile("s_waitcnt vmcnt(0)" ::: "memory");
;         __hip_atomic_fetch_add(ctr, 1u, __ATOMIC_RELAXED, __HIP_MEMORY_SCOPE_AGENT);
;         while (__hip_atomic_load(ctr, __ATOMIC_RELAXED, __HIP_MEMORY_SCOPE_AGENT) < gen * G) __builtin_amdgcn_s_sleep(32);
;         __builtin_amdgcn_fence(__ATOMIC_ACQUIRE, "agent");
;         asm volatile("s_waitcnt vmcnt(0)" ::: "memory");
;     }
;     __syncthreads();
; }
; __global__ void __launch_bounds__(NTHREADS) fwd_megakernel(Params p) {
;     ...
;     SYNC(3)
.LBB0_1391:
	s_or_b64 exec, exec, s[72:73]
	v_cmp_gt_i32_e32 vcc, 4, v1
	v_cmp_lt_i32_e64 s[2:3], 4, v5
	s_and_b64 s[0:1], vcc, s[2:3]
	s_and_saveexec_b64 s[2:3], s[0:1]
	s_cbranch_execz .LBB0_1400
	s_waitcnt vmcnt(0)
	v_and_b32_e32 v2, 0x3ff, v0
	v_add_u32_e32 v210, 1, v210
	v_cmp_eq_u32_e32 vcc, 0, v2
	s_waitcnt vmcnt(0)
	s_barrier
	s_and_saveexec_b64 s[4:5], vcc
	s_cbranch_execz .LBB0_1399
	s_getreg_b32 s1, hwreg(HW_REG_XCC_ID, 0, 4)
	s_lshl_b32 s1, s1, 8
	s_add_u32 s12, s42, 0x600000
	s_addc_u32 s13, s43, 0
	s_add_u32 s12, s12, s1
	s_addc_u32 s13, s13, 0
	s_add_u32 s14, s42, 0x601000
	s_addc_u32 s15, s43, 0
	s_lshr_b32 s16, s86, 3
	v_mov_b32_e32 v2, 0
	v_mov_b32_e32 v3, 1
	v_mov_b32_e32 v7, v210
	global_atomic_add v4, v2, v3, s[12:13] sc0
	v_mul_lo_u32 v8, v7, s16
	s_mov_b32 s0, 0
	s_waitcnt vmcnt(0)
	v_add_u32_e32 v4, 1, v4
	v_cmp_eq_u32_e32 vcc, v4, v8
	s_cbranch_vccz .Lxb_nl_2
	buffer_wbl2 sc1
	s_waitcnt vmcnt(0)
	global_atomic_add v4, v2, v3, s[14:15] sc0
	v_lshlrev_b32_e32 v8, 3, v7
	s_waitcnt vmcnt(0)
	v_add_u32_e32 v4, 1, v4
	v_cmp_eq_u32_e32 vcc, v4, v8
	s_cbranch_vccz .Lxb_wt_2
	global_atomic_add v2, v3, s[14:15] offset:256
	s_branch .Lxb_lr_2

; #define SYNC(k) if (p.ph_lo <= (k) && (k) + 1 < p.ph_hi) { if ((k) == 0) grid.sync(); else gbar(bctr, bgen, gridDim.x); }
; DI void gbar(unsigned* ctr, unsigned& gen, unsigned G) {
;     ...
;         asm volatile("s_waitcnt vmcnt(0)" ::: "memory");
;     }
;     __syncthreads();
; __global__ void __launch_bounds__(NTHREADS) fwd_megakernel(Params p) {
;     ...
;     SYNC(3)
.Lxb_na_2:
	buffer_inv sc1
	s_waitcnt vmcnt(0)
.Lxb_dn_2:
	v_mov_b32_e32 v1, s90
	v_mov_b32_e32 v5, s91
.LBB0_1399:
	s_or_b64 exec, exec, s[4:5]
	s_barrier

; #define SYNC(k) if (p.ph_lo <= (k) && (k) + 1 < p.ph_hi) { if ((k) == 0) grid.sync(); else gbar(bctr, bgen, gridDim.x); }
; DI void gbar(unsigned* ctr, unsigned& gen, unsigned G) {
;     asm volatile("s_waitcnt vmcnt(0)" ::: "memory");
;     __syncthreads();
;     gen += 1;
;     if (threadIdx.x == 0) {
;         __builtin_amdgcn_fence(__ATOMIC_RELEASE, "agent");
;         asm volatile("s_waitcnt vmcnt(0)" ::: "memory");
;         __hip_atomic_fetch_add(ctr, 1u, __ATOMIC_RELAXED, __HIP_MEMORY_SCOPE_AGENT);
;         while (__hip_atomic_load(ctr, __ATOMIC_RELAXED, __HIP_MEMORY_SCOPE_AGENT) < gen * G) __builtin_amdgcn_s_sleep(32);
;         __builtin_amdgcn_fence(__ATOMIC_ACQUIRE, "agent");
;         asm volatile("s_waitcnt vmcnt(0)" ::: "memory");
;     }
;     __syncthreads();
; }
; __global__ void __launch_bounds__(NTHREADS) fwd_megakernel(Params p) {
;     ...
;     SYNC(4)
.LBB0_1445:
	s_or_b64 exec, exec, s[6:7]
	v_cmp_gt_i32_e32 vcc, 5, v1
	v_cmp_lt_i32_e64 s[2:3], 5, v5
	s_and_b64 s[0:1], vcc, s[2:3]
	s_and_saveexec_b64 s[2:3], s[0:1]
	s_cbranch_execz .LBB0_1454
	s_waitcnt vmcnt(0)
	v_and_b32_e32 v2, 0x3ff, v0
	v_add_u32_e32 v210, 1, v210
	v_cmp_eq_u32_e32 vcc, 0, v2
	s_waitcnt vmcnt(0) lgkmcnt(0)
	s_barrier
	s_and_saveexec_b64 s[4:5], vcc
	s_cbranch_execz .LBB0_1453
	s_getreg_b32 s1, hwreg(HW_REG_XCC_ID, 0, 4)
	s_lshl_b32 s1, s1, 8
	s_add_u32 s12, s42, 0x600000
	s_addc_u32 s13, s43, 0
	s_add_u32 s12, s12, s1
	s_addc_u32 s13, s13, 0
	s_add_u32 s14, s42, 0x601000
	s_addc_u32 s15, s43, 0
	s_lshr_b32 s16, s86, 3
	v_mov_b32_e32 v2, 0
	v_mov_b32_e32 v3, 1
	v_mov_b32_e32 v7, v210
	global_atomic_add v4, v2, v3, s[12:13] sc0
	v_mul_lo_u32 v8, v7, s16
	s_mov_b32 s0, 0
	s_waitcnt vmcnt(0)
	v_add_u32_e32 v4, 1, v4
	v_cmp_eq_u32_e32 vcc, v4, v8
	s_cbranch_vccz .Lxb_nl_3
	buffer_wbl2 sc1
	s_waitcnt vmcnt(0)
	global_atomic_add v4, v2, v3, s[14:15] sc0
	v_lshlrev_b32_e32 v8, 3, v7
	s_waitcnt vmcnt(0)
	v_add_u32_e32 v4, 1, v4
	v_cmp_eq_u32_e32 vcc, v4, v8
	s_cbranch_vccz .Lxb_wt_3
	global_atomic_add v2, v3, s[14:15] offset:256
	s_branch .Lxb_lr_3

; #define SYNC(k) if (p.ph_lo <= (k) && (k) + 1 < p.ph_hi) { if ((k) == 0) grid.sync(); else gbar(bctr, bgen, gridDim.x); }
; DI void gbar(unsigned* ctr, unsigned& gen, unsigned G) {
;     ...
;         asm volatile("s_waitcnt vmcnt(0)" ::: "memory");
;     }
;     __syncthreads();
; __global__ void __launch_bounds__(NTHREADS) fwd_megakernel(Params p) {
;     ...
;     SYNC(4)
.Lxb_na_3:
	buffer_inv sc1
	s_waitcnt vmcnt(0)
.Lxb_dn_3:
	v_mov_b32_e32 v1, s90
	v_mov_b32_e32 v5, s91
.LBB0_1453:
	s_or_b64 exec, exec, s[4:5]
	s_barrier

; #define SYNC(k) if (p.ph_lo <= (k) && (k) + 1 < p.ph_hi) { if ((k) == 0) grid.sync(); else gbar(bctr, bgen, gridDim.x); }
; DI void gbar(unsigned* ctr, unsigned& gen, unsigned G) {
;     asm volatile("s_waitcnt vmcnt(0)" ::: "memory");
;     __syncthreads();
;     gen += 1;
;     if (threadIdx.x == 0) {
;         __builtin_amdgcn_fence(__ATOMIC_RELEASE, "agent");
;         asm volatile("s_waitcnt vmcnt(0)" ::: "memory");
;         __hip_atomic_fetch_add(ctr, 1u, __ATOMIC_RELAXED, __HIP_MEMORY_SCOPE_AGENT);
;         while (__hip_atomic_load(ctr, __ATOMIC_RELAXED, __HIP_MEMORY_SCOPE_AGENT) < gen * G) __builtin_amdgcn_s_sleep(32);
;         __builtin_amdgcn_fence(__ATOMIC_ACQUIRE, "agent");
;         asm volatile("s_waitcnt vmcnt(0)" ::: "memory");
;     }
;     __syncthreads();
; }
; __global__ void __launch_bounds__(NTHREADS) fwd_megakernel(Params p) {
;     ...
;     SYNC(5)
.LBB0_1479:
	s_or_b64 exec, exec, s[4:5]
	v_cmp_gt_i32_e32 vcc, 6, v1
	v_cmp_lt_i32_e64 s[2:3], 6, v5
	s_and_b64 s[0:1], vcc, s[2:3]
	s_and_saveexec_b64 s[2:3], s[0:1]
	s_cbranch_execz .LBB0_1488
	s_waitcnt vmcnt(0)
	v_and_b32_e32 v2, 0x3ff, v0
	v_add_u32_e32 v210, 1, v210
	v_cmp_eq_u32_e32 vcc, 0, v2
	s_waitcnt vmcnt(0) lgkmcnt(0)
	s_barrier
	s_and_saveexec_b64 s[4:5], vcc
	s_cbranch_execz .LBB0_1487
	s_getreg_b32 s1, hwreg(HW_REG_XCC_ID, 0, 4)
	s_lshl_b32 s1, s1, 8
	s_add_u32 s12, s42, 0x600000
	s_addc_u32 s13, s43, 0
	s_add_u32 s12, s12, s1
	s_addc_u32 s13, s13, 0
	s_add_u32 s14, s42, 0x601000
	s_addc_u32 s15, s43, 0
	s_lshr_b32 s16, s86, 3
	v_mov_b32_e32 v2, 0
	v_mov_b32_e32 v3, 1
	v_mov_b32_e32 v7, v210
	global_atomic_add v4, v2, v3, s[12:13] sc0
	v_mul_lo_u32 v8, v7, s16
	s_mov_b32 s0, 0
	s_waitcnt vmcnt(0)
	v_add_u32_e32 v4, 1, v4
	v_cmp_eq_u32_e32 vcc, v4, v8
	s_cbranch_vccz .Lxb_nl_4
	buffer_wbl2 sc1
	s_waitcnt vmcnt(0)
	global_atomic_add v4, v2, v3, s[14:15] sc0
	v_lshlrev_b32_e32 v8, 3, v7
	s_waitcnt vmcnt(0)
	v_add_u32_e32 v4, 1, v4
	v_cmp_eq_u32_e32 vcc, v4, v8
	s_cbranch_vccz .Lxb_wt_4
	global_atomic_add v2, v3, s[14:15] offset:256
	s_branch .Lxb_lr_4

; #define SYNC(k) if (p.ph_lo <= (k) && (k) + 1 < p.ph_hi) { if ((k) == 0) grid.sync(); else gbar(bctr, bgen, gridDim.x); }
; DI void gbar(unsigned* ctr, unsigned& gen, unsigned G) {
;     ...
;         asm volatile("s_waitcnt vmcnt(0)" ::: "memory");
;     }
;     __syncthreads();
; __global__ void __launch_bounds__(NTHREADS) fwd_megakernel(Params p) {
;     ...
;     SYNC(5)
.Lxb_na_4:
	buffer_inv sc1
	s_waitcnt vmcnt(0)
.Lxb_dn_4:
	v_mov_b32_e32 v1, s90
	v_mov_b32_e32 v5, s91
.LBB0_1487:
	s_or_b64 exec, exec, s[4:5]
	s_barrier

; #define PH(k) if (p.ph_lo <= (k) && (k) < p.ph_hi)
; #define GEMM(EPI, e, A_, W_, N_, K_) { pg8::Gemm g{A_, W_, T_TOK, N_, K_}; pg8::StaticOrder S; S.init(T_TOK, N_, (int)gridDim.x, (int)blockIdx.x); \
;         pg8::gemm_phase<EPI, pg8::StaticOrder, true, true>(l3, g, S, e); }
; DI void gbar(unsigned* ctr, unsigned& gen, unsigned G) {
;     asm volatile("s_waitcnt vmcnt(0)" ::: "memory");
;     __syncthreads();
;     gen += 1;
;     if (threadIdx.x == 0) {
;         __builtin_amdgcn_fence(__ATOMIC_RELEASE, "agent");
;         asm volatile("s_waitcnt vmcnt(0)" ::: "memory");
;         __hip_atomic_fetch_add(ctr, 1u, __ATOMIC_RELAXED, __HIP_MEMORY_SCOPE_AGENT);
;         while (__hip_atomic_load(ctr, __ATOMIC_RELAXED, __HIP_MEMORY_SCOPE_AGENT) < gen * G) __builtin_amdgcn_s_sleep(32);
;         __builtin_amdgcn_fence(__ATOMIC_ACQUIRE, "agent");
;         asm volatile("s_waitcnt vmcnt(0)" ::: "memory");
;     }
;     __syncthreads();
; }
; __global__ void __launch_bounds__(NTHREADS) fwd_megakernel(Params p) {
;     ...
;     PH(7) { EpiProj1b e{sumsq + 2 * T_TOK, pbuf, vt, (float*)(ws + WS_BITMASK), (float*)(ws + WS_IW), rope}; GEMM(EpiProj1b, e, hb, (const bf16_t*)(ws + WS_WT_IN1), 3840, 1024) }
.LBB0_1531:
	s_or_b64 exec, exec, s[6:7]
	v_cmp_gt_i32_e32 vcc, 7, v1
	v_cmp_lt_i32_e64 s[2:3], 7, v5
	s_and_b64 s[0:1], vcc, s[2:3]
	s_and_saveexec_b64 s[2:3], s[0:1]
	s_cbranch_execz .LBB0_1540
	s_waitcnt vmcnt(0)
	v_and_b32_e32 v2, 0x3ff, v0
	v_add_u32_e32 v210, 1, v210
	v_cmp_eq_u32_e32 vcc, 0, v2
	s_waitcnt vmcnt(0) lgkmcnt(0)
	s_barrier
	s_and_saveexec_b64 s[4:5], vcc
	s_cbranch_execz .LBB0_1539
	s_getreg_b32 s1, hwreg(HW_REG_XCC_ID, 0, 4)
	s_lshl_b32 s1, s1, 8
	s_add_u32 s12, s42, 0x600000
	s_addc_u32 s13, s43, 0
	s_add_u32 s12, s12, s1
	s_addc_u32 s13, s13, 0
	s_add_u32 s14, s42, 0x601000
	s_addc_u32 s15, s43, 0
	s_lshr_b32 s16, s86, 3
	v_mov_b32_e32 v2, 0
	v_mov_b32_e32 v3, 1
	v_mov_b32_e32 v7, v210
	global_atomic_add v4, v2, v3, s[12:13] sc0
	v_mul_lo_u32 v8, v7, s16
	s_mov_b32 s0, 0
	s_waitcnt vmcnt(0)
	v_add_u32_e32 v4, 1, v4
	v_cmp_eq_u32_e32 vcc, v4, v8
	s_cbranch_vccz .Lxb_nl_5
	buffer_wbl2 sc1
	s_waitcnt vmcnt(0)
	global_atomic_add v4, v2, v3, s[14:15] sc0
	v_lshlrev_b32_e32 v8, 3, v7
	s_waitcnt vmcnt(0)
	v_add_u32_e32 v4, 1, v4
	v_cmp_eq_u32_e32 vcc, v4, v8
	s_cbranch_vccz .Lxb_wt_5
	global_atomic_add v2, v3, s[14:15] offset:256
	s_branch .Lxb_lr_5

; #define PH(k) if (p.ph_lo <= (k) && (k) < p.ph_hi)
; #define GEMM(EPI, e, A_, W_, N_, K_) { pg8::Gemm g{A_, W_, T_TOK, N_, K_}; pg8::StaticOrder S; S.init(T_TOK, N_, (int)gridDim.x, (int)blockIdx.x); \
;         pg8::gemm_phase<EPI, pg8::StaticOrder, true, true>(l3, g, S, e); }
; DI void gbar(unsigned* ctr, unsigned& gen, unsigned G) {
;     ...
;         asm volatile("s_waitcnt vmcnt(0)" ::: "memory");
;     }
;     __syncthreads();
; __global__ void __launch_bounds__(NTHREADS) fwd_megakernel(Params p) {
;     ...
;     PH(7) { EpiProj1b e{sumsq + 2 * T_TOK, pbuf, vt, (float*)(ws + WS_BITMASK), (float*)(ws + WS_IW), rope}; GEMM(EpiProj1b, e, hb, (const bf16_t*)(ws + WS_WT_IN1), 3840, 1024) }
.Lxb_na_5:
	buffer_inv sc1
	s_waitcnt vmcnt(0)
.Lxb_dn_5:
	v_mov_b32_e32 v1, s90
	v_mov_b32_e32 v5, s91
.LBB0_1539:
	s_or_b64 exec, exec, s[4:5]
	s_barrier

; #define SYNC(k) if (p.ph_lo <= (k) && (k) + 1 < p.ph_hi) { if ((k) == 0) grid.sync(); else gbar(bctr, bgen, gridDim.x); }
; DI void gbar(unsigned* ctr, unsigned& gen, unsigned G) {
;     asm volatile("s_waitcnt vmcnt(0)" ::: "memory");
;     __syncthreads();
;     gen += 1;
;     if (threadIdx.x == 0) {
;         __builtin_amdgcn_fence(__ATOMIC_RELEASE, "agent");
;         asm volatile("s_waitcnt vmcnt(0)" ::: "memory");
;         __hip_atomic_fetch_add(ctr, 1u, __ATOMIC_RELAXED, __HIP_MEMORY_SCOPE_AGENT);
;         while (__hip_atomic_load(ctr, __ATOMIC_RELAXED, __HIP_MEMORY_SCOPE_AGENT) < gen * G) __builtin_amdgcn_s_sleep(32);
;         __builtin_amdgcn_fence(__ATOMIC_ACQUIRE, "agent");
;         asm volatile("s_waitcnt vmcnt(0)" ::: "memory");
;     }
;     __syncthreads();
; }
; __global__ void __launch_bounds__(NTHREADS) fwd_megakernel(Params p) {
;     ...
;     SYNC(7)
.LBB0_2532:
	s_or_b64 exec, exec, s[12:13]
	v_cmp_gt_i32_e32 vcc, 8, v1
	v_cmp_lt_i32_e64 s[2:3], 8, v5
	s_and_b64 s[0:1], vcc, s[2:3]
	s_and_saveexec_b64 s[2:3], s[0:1]
	s_cbranch_execz .LBB0_2541
	s_waitcnt vmcnt(0)
	v_and_b32_e32 v2, 0x3ff, v0
	v_add_u32_e32 v210, 1, v210
	v_cmp_eq_u32_e32 vcc, 0, v2
	s_waitcnt vmcnt(0) lgkmcnt(0)
	s_barrier
	s_and_saveexec_b64 s[4:5], vcc
	s_cbranch_execz .LBB0_2540
	s_getreg_b32 s1, hwreg(HW_REG_XCC_ID, 0, 4)
	s_lshl_b32 s1, s1, 8
	s_add_u32 s12, s42, 0x600000
	s_addc_u32 s13, s43, 0
	s_add_u32 s12, s12, s1
	s_addc_u32 s13, s13, 0
	s_add_u32 s14, s42, 0x601000
	s_addc_u32 s15, s43, 0
	s_lshr_b32 s16, s86, 3
	v_mov_b32_e32 v2, 0
	v_mov_b32_e32 v3, 1
	v_mov_b32_e32 v7, v210
	global_atomic_add v4, v2, v3, s[12:13] sc0
	v_mul_lo_u32 v8, v7, s16
	s_mov_b32 s0, 0
	s_waitcnt vmcnt(0)
	v_add_u32_e32 v4, 1, v4
	v_cmp_eq_u32_e32 vcc, v4, v8
	s_cbranch_vccz .Lxb_nl_6
	buffer_wbl2 sc1
	s_waitcnt vmcnt(0)
	global_atomic_add v4, v2, v3, s[14:15] sc0
	v_lshlrev_b32_e32 v8, 3, v7
	s_waitcnt vmcnt(0)
	v_add_u32_e32 v4, 1, v4
	v_cmp_eq_u32_e32 vcc, v4, v8
	s_cbranch_vccz .Lxb_wt_6
	global_atomic_add v2, v3, s[14:15] offset:256
	s_branch .Lxb_lr_6

; #define SYNC(k) if (p.ph_lo <= (k) && (k) + 1 < p.ph_hi) { if ((k) == 0) grid.sync(); else gbar(bctr, bgen, gridDim.x); }
; DI void gbar(unsigned* ctr, unsigned& gen, unsigned G) {
;     ...
;         asm volatile("s_waitcnt vmcnt(0)" ::: "memory");
;     }
;     __syncthreads();
; __global__ void __launch_bounds__(NTHREADS) fwd_megakernel(Params p) {
;     ...
;     SYNC(7)
.Lxb_na_6:
	buffer_inv sc1
	s_waitcnt vmcnt(0)
.Lxb_dn_6:
	v_mov_b32_e32 v1, s90
	v_mov_b32_e32 v5, s91
.LBB0_2540:
	s_or_b64 exec, exec, s[4:5]
	s_barrier

; #define SYNC(k) if (p.ph_lo <= (k) && (k) + 1 < p.ph_hi) { if ((k) == 0) grid.sync(); else gbar(bctr, bgen, gridDim.x); }
; DI void gbar(unsigned* ctr, unsigned& gen, unsigned G) {
;     asm volatile("s_waitcnt vmcnt(0)" ::: "memory");
;     __syncthreads();
;     gen += 1;
;     if (threadIdx.x == 0) {
;         __builtin_amdgcn_fence(__ATOMIC_RELEASE, "agent");
;         asm volatile("s_waitcnt vmcnt(0)" ::: "memory");
;         __hip_atomic_fetch_add(ctr, 1u, __ATOMIC_RELAXED, __HIP_MEMORY_SCOPE_AGENT);
;         while (__hip_atomic_load(ctr, __ATOMIC_RELAXED, __HIP_MEMORY_SCOPE_AGENT) < gen * G) __builtin_amdgcn_s_sleep(32);
;         __builtin_amdgcn_fence(__ATOMIC_ACQUIRE, "agent");
;         asm volatile("s_waitcnt vmcnt(0)" ::: "memory");
;     }
;     __syncthreads();
; }
; __global__ void __launch_bounds__(NTHREADS) fwd_megakernel(Params p) {
;     ...
;     SYNC(8)
.LBB0_2545:
	s_or_b64 exec, exec, s[8:9]
	v_cmp_lt_i32_e64 s[2:3], 9, v5
	s_and_b64 s[0:1], vcc, s[2:3]
	s_and_saveexec_b64 s[2:3], s[0:1]
	s_cbranch_execz .LBB0_2554
	s_waitcnt vmcnt(0)
	v_and_b32_e32 v2, 0x3ff, v0
	v_add_u32_e32 v210, 1, v210
	v_cmp_eq_u32_e32 vcc, 0, v2
	s_waitcnt vmcnt(0)
	s_barrier
	s_and_saveexec_b64 s[4:5], vcc
	s_cbranch_execz .LBB0_2553
	s_getreg_b32 s1, hwreg(HW_REG_XCC_ID, 0, 4)
	s_lshl_b32 s1, s1, 8
	s_add_u32 s12, s42, 0x600000
	s_addc_u32 s13, s43, 0
	s_add_u32 s12, s12, s1
	s_addc_u32 s13, s13, 0
	s_add_u32 s14, s42, 0x601000
	s_addc_u32 s15, s43, 0
	s_lshr_b32 s16, s86, 3
	v_mov_b32_e32 v2, 0
	v_mov_b32_e32 v3, 1
	v_mov_b32_e32 v7, v210
	global_atomic_add v4, v2, v3, s[12:13] sc0
	v_mul_lo_u32 v8, v7, s16
	s_mov_b32 s0, 0
	s_waitcnt vmcnt(0)
	v_add_u32_e32 v4, 1, v4
	v_cmp_eq_u32_e32 vcc, v4, v8
	s_cbranch_vccz .Lxb_nl_7
	buffer_wbl2 sc1
	s_waitcnt vmcnt(0)
	global_atomic_add v4, v2, v3, s[14:15] sc0
	v_lshlrev_b32_e32 v8, 3, v7
	s_waitcnt vmcnt(0)
	v_add_u32_e32 v4, 1, v4
	v_cmp_eq_u32_e32 vcc, v4, v8
	s_cbranch_vccz .Lxb_wt_7
	global_atomic_add v2, v3, s[14:15] offset:256
	s_branch .Lxb_lr_7

; #define SYNC(k) if (p.ph_lo <= (k) && (k) + 1 < p.ph_hi) { if ((k) == 0) grid.sync(); else gbar(bctr, bgen, gridDim.x); }
; DI void gbar(unsigned* ctr, unsigned& gen, unsigned G) {
;     ...
;         asm volatile("s_waitcnt vmcnt(0)" ::: "memory");
;     }
;     __syncthreads();
; __global__ void __launch_bounds__(NTHREADS) fwd_megakernel(Params p) {
;     ...
;     SYNC(8)
.Lxb_na_7:
	buffer_inv sc1
	s_waitcnt vmcnt(0)
.Lxb_dn_7:
	v_mov_b32_e32 v1, s90
	v_mov_b32_e32 v5, s91
.LBB0_2553:
	s_or_b64 exec, exec, s[4:5]
	s_barrier

; #define SYNC(k) if (p.ph_lo <= (k) && (k) + 1 < p.ph_hi) { if ((k) == 0) grid.sync(); else gbar(bctr, bgen, gridDim.x); }
; DI void gbar(unsigned* ctr, unsigned& gen, unsigned G) {
;     asm volatile("s_waitcnt vmcnt(0)" ::: "memory");
;     __syncthreads();
;     gen += 1;
;     if (threadIdx.x == 0) {
;         __builtin_amdgcn_fence(__ATOMIC_RELEASE, "agent");
;         asm volatile("s_waitcnt vmcnt(0)" ::: "memory");
;         __hip_atomic_fetch_add(ctr, 1u, __ATOMIC_RELAXED, __HIP_MEMORY_SCOPE_AGENT);
;         while (__hip_atomic_load(ctr, __ATOMIC_RELAXED, __HIP_MEMORY_SCOPE_AGENT) < gen * G) __builtin_amdgcn_s_sleep(32);
;         __builtin_amdgcn_fence(__ATOMIC_ACQUIRE, "agent");
;         asm volatile("s_waitcnt vmcnt(0)" ::: "memory");
;     }
;     __syncthreads();
; }
; __global__ void __launch_bounds__(NTHREADS) fwd_megakernel(Params p) {
;     ...
;     SYNC(9)
.LBB0_3580:
	s_or_b64 exec, exec, s[2:3]
	v_cmp_gt_i32_e32 vcc, 10, v1
	v_cmp_lt_i32_e64 s[2:3], 10, v5
	s_and_b64 s[0:1], vcc, s[2:3]
	s_and_saveexec_b64 s[2:3], s[0:1]
	s_cbranch_execz .LBB0_3589
	s_waitcnt vmcnt(0)
	v_and_b32_e32 v2, 0x3ff, v0
	v_add_u32_e32 v210, 1, v210
	v_cmp_eq_u32_e32 vcc, 0, v2
	s_waitcnt vmcnt(0)
	s_barrier
	s_and_saveexec_b64 s[4:5], vcc
	s_cbranch_execz .LBB0_3588
	s_getreg_b32 s1, hwreg(HW_REG_XCC_ID, 0, 4)
	s_lshl_b32 s1, s1, 8
	s_add_u32 s12, s42, 0x600000
	s_addc_u32 s13, s43, 0
	s_add_u32 s12, s12, s1
	s_addc_u32 s13, s13, 0
	s_add_u32 s14, s42, 0x601000
	s_addc_u32 s15, s43, 0
	s_lshr_b32 s16, s86, 3
	v_mov_b32_e32 v2, 0
	v_mov_b32_e32 v3, 1
	v_mov_b32_e32 v7, v210
	global_atomic_add v4, v2, v3, s[12:13] sc0
	v_mul_lo_u32 v8, v7, s16
	s_mov_b32 s0, 0
	s_waitcnt vmcnt(0)
	v_add_u32_e32 v4, 1, v4
	v_cmp_eq_u32_e32 vcc, v4, v8
	s_cbranch_vccz .Lxb_nl_8
	buffer_wbl2 sc1
	s_waitcnt vmcnt(0)
	global_atomic_add v4, v2, v3, s[14:15] sc0
	v_lshlrev_b32_e32 v8, 3, v7
	s_waitcnt vmcnt(0)
	v_add_u32_e32 v4, 1, v4
	v_cmp_eq_u32_e32 vcc, v4, v8
	s_cbranch_vccz .Lxb_wt_8
	global_atomic_add v2, v3, s[14:15] offset:256
	s_branch .Lxb_lr_8

; #define SYNC(k) if (p.ph_lo <= (k) && (k) + 1 < p.ph_hi) { if ((k) == 0) grid.sync(); else gbar(bctr, bgen, gridDim.x); }
; DI void gbar(unsigned* ctr, unsigned& gen, unsigned G) {
;     ...
;         asm volatile("s_waitcnt vmcnt(0)" ::: "memory");
;     }
;     __syncthreads();
; __global__ void __launch_bounds__(NTHREADS) fwd_megakernel(Params p) {
;     ...
;     SYNC(9)
.Lxb_na_8:
	buffer_inv sc1
	s_waitcnt vmcnt(0)
.Lxb_dn_8:
	v_mov_b32_e32 v1, s90
	v_mov_b32_e32 v5, s91
.LBB0_3588:
	s_or_b64 exec, exec, s[4:5]
	s_barrier

; #define SYNC(k) if (p.ph_lo <= (k) && (k) + 1 < p.ph_hi) { if ((k) == 0) grid.sync(); else gbar(bctr, bgen, gridDim.x); }
; DI void gbar(unsigned* ctr, unsigned& gen, unsigned G) {
;     asm volatile("s_waitcnt vmcnt(0)" ::: "memory");
;     __syncthreads();
;     gen += 1;
;     if (threadIdx.x == 0) {
;         __builtin_amdgcn_fence(__ATOMIC_RELEASE, "agent");
;         asm volatile("s_waitcnt vmcnt(0)" ::: "memory");
;         __hip_atomic_fetch_add(ctr, 1u, __ATOMIC_RELAXED, __HIP_MEMORY_SCOPE_AGENT);
;         while (__hip_atomic_load(ctr, __ATOMIC_RELAXED, __HIP_MEMORY_SCOPE_AGENT) < gen * G) __builtin_amdgcn_s_sleep(32);
;         __builtin_amdgcn_fence(__ATOMIC_ACQUIRE, "agent");
;         asm volatile("s_waitcnt vmcnt(0)" ::: "memory");
;     }
;     __syncthreads();
; }
; __global__ void __launch_bounds__(NTHREADS) fwd_megakernel(Params p) {
;     ...
;     SYNC(10)
.LBB0_3644:
	s_or_b64 exec, exec, s[8:9]
	v_cmp_gt_i32_e32 vcc, 11, v1
	v_cmp_lt_i32_e64 s[2:3], 11, v5
	s_and_b64 s[0:1], vcc, s[2:3]
	s_and_saveexec_b64 s[2:3], s[0:1]
	s_cbranch_execz .LBB0_3653
	s_waitcnt vmcnt(0)
	v_and_b32_e32 v2, 0x3ff, v0
	v_add_u32_e32 v210, 1, v210
	v_cmp_eq_u32_e32 vcc, 0, v2
	s_waitcnt vmcnt(0)
	s_barrier
	s_and_saveexec_b64 s[4:5], vcc
	s_cbranch_execz .LBB0_3652
	s_getreg_b32 s1, hwreg(HW_REG_XCC_ID, 0, 4)
	s_lshl_b32 s1, s1, 8
	s_add_u32 s12, s42, 0x600000
	s_addc_u32 s13, s43, 0
	s_add_u32 s12, s12, s1
	s_addc_u32 s13, s13, 0
	s_add_u32 s14, s42, 0x601000
	s_addc_u32 s15, s43, 0
	s_lshr_b32 s16, s86, 3
	v_mov_b32_e32 v2, 0
	v_mov_b32_e32 v3, 1
	v_mov_b32_e32 v7, v210
	global_atomic_add v4, v2, v3, s[12:13] sc0
	v_mul_lo_u32 v8, v7, s16
	s_mov_b32 s0, 0
	s_waitcnt vmcnt(0)
	v_add_u32_e32 v4, 1, v4
	v_cmp_eq_u32_e32 vcc, v4, v8
	s_cbranch_vccz .Lxb_nl_9
	buffer_wbl2 sc1
	s_waitcnt vmcnt(0)
	global_atomic_add v4, v2, v3, s[14:15] sc0
	v_lshlrev_b32_e32 v8, 3, v7
	s_waitcnt vmcnt(0)
	v_add_u32_e32 v4, 1, v4
	v_cmp_eq_u32_e32 vcc, v4, v8
	s_cbranch_vccz .Lxb_wt_9
	global_atomic_add v2, v3, s[14:15] offset:256
	s_branch .Lxb_lr_9

; #define SYNC(k) if (p.ph_lo <= (k) && (k) + 1 < p.ph_hi) { if ((k) == 0) grid.sync(); else gbar(bctr, bgen, gridDim.x); }
; DI void gbar(unsigned* ctr, unsigned& gen, unsigned G) {
;     ...
;         asm volatile("s_waitcnt vmcnt(0)" ::: "memory");
;     }
;     __syncthreads();
; __global__ void __launch_bounds__(NTHREADS) fwd_megakernel(Params p) {
;     ...
;     SYNC(10)
.Lxb_na_9:
	buffer_inv sc1
	s_waitcnt vmcnt(0)
.Lxb_dn_9:
	v_mov_b32_e32 v1, s90
	v_mov_b32_e32 v5, s91
.LBB0_3652:
	s_or_b64 exec, exec, s[4:5]
	s_barrier

; #define SYNC(k) if (p.ph_lo <= (k) && (k) + 1 < p.ph_hi) { if ((k) == 0) grid.sync(); else gbar(bctr, bgen, gridDim.x); }
; DI void gbar(unsigned* ctr, unsigned& gen, unsigned G) {
;     asm volatile("s_waitcnt vmcnt(0)" ::: "memory");
;     __syncthreads();
;     gen += 1;
;     if (threadIdx.x == 0) {
;         __builtin_amdgcn_fence(__ATOMIC_RELEASE, "agent");
;         asm volatile("s_waitcnt vmcnt(0)" ::: "memory");
;         __hip_atomic_fetch_add(ctr, 1u, __ATOMIC_RELAXED, __HIP_MEMORY_SCOPE_AGENT);
;         while (__hip_atomic_load(ctr, __ATOMIC_RELAXED, __HIP_MEMORY_SCOPE_AGENT) < gen * G) __builtin_amdgcn_s_sleep(32);
;         __builtin_amdgcn_fence(__ATOMIC_ACQUIRE, "agent");
;         asm volatile("s_waitcnt vmcnt(0)" ::: "memory");
;     }
;     __syncthreads();
; }
; __global__ void __launch_bounds__(NTHREADS) fwd_megakernel(Params p) {
;     ...
;     SYNC(11)
.LBB0_3696:
	s_or_b64 exec, exec, s[6:7]
	v_cmp_gt_i32_e32 vcc, 12, v1
	v_cmp_lt_i32_e64 s[2:3], 12, v5
	s_and_b64 s[0:1], vcc, s[2:3]
	s_and_saveexec_b64 s[2:3], s[0:1]
	s_cbranch_execz .LBB0_3705
	s_waitcnt vmcnt(0)
	v_and_b32_e32 v2, 0x3ff, v0
	v_add_u32_e32 v210, 1, v210
	v_cmp_eq_u32_e32 vcc, 0, v2
	s_waitcnt vmcnt(0) lgkmcnt(0)
	s_barrier
	s_and_saveexec_b64 s[4:5], vcc
	s_cbranch_execz .LBB0_3704
	s_getreg_b32 s1, hwreg(HW_REG_XCC_ID, 0, 4)
	s_lshl_b32 s1, s1, 8
	s_add_u32 s12, s42, 0x600000
	s_addc_u32 s13, s43, 0
	s_add_u32 s12, s12, s1
	s_addc_u32 s13, s13, 0
	s_add_u32 s14, s42, 0x601000
	s_addc_u32 s15, s43, 0
	s_lshr_b32 s16, s86, 3
	v_mov_b32_e32 v2, 0
	v_mov_b32_e32 v3, 1
	v_mov_b32_e32 v7, v210
	global_atomic_add v4, v2, v3, s[12:13] sc0
	v_mul_lo_u32 v8, v7, s16
	s_mov_b32 s0, 0
	s_waitcnt vmcnt(0)
	v_add_u32_e32 v4, 1, v4
	v_cmp_eq_u32_e32 vcc, v4, v8
	s_cbranch_vccz .Lxb_nl_10
	buffer_wbl2 sc1
	s_waitcnt vmcnt(0)
	global_atomic_add v4, v2, v3, s[14:15] sc0
	v_lshlrev_b32_e32 v8, 3, v7
	s_waitcnt vmcnt(0)
	v_add_u32_e32 v4, 1, v4
	v_cmp_eq_u32_e32 vcc, v4, v8
	s_cbranch_vccz .Lxb_wt_10
	global_atomic_add v2, v3, s[14:15] offset:256
	s_branch .Lxb_lr_10

; #define SYNC(k) if (p.ph_lo <= (k) && (k) + 1 < p.ph_hi) { if ((k) == 0) grid.sync(); else gbar(bctr, bgen, gridDim.x); }
; DI void gbar(unsigned* ctr, unsigned& gen, unsigned G) {
;     ...
;         asm volatile("s_waitcnt vmcnt(0)" ::: "memory");
;     }
;     __syncthreads();
; __global__ void __launch_bounds__(NTHREADS) fwd_megakernel(Params p) {
;     ...
;     SYNC(11)
.Lxb_na_10:
	buffer_inv sc1
	s_waitcnt vmcnt(0)
.Lxb_dn_10:
	v_mov_b32_e32 v1, s90
	v_mov_b32_e32 v5, s91
.LBB0_3704:
	s_or_b64 exec, exec, s[4:5]
	s_barrier

; #define SYNC(k) if (p.ph_lo <= (k) && (k) + 1 < p.ph_hi) { if ((k) == 0) grid.sync(); else gbar(bctr, bgen, gridDim.x); }
; DI void gbar(unsigned* ctr, unsigned& gen, unsigned G) {
;     asm volatile("s_waitcnt vmcnt(0)" ::: "memory");
;     __syncthreads();
;     gen += 1;
;     if (threadIdx.x == 0) {
;         __builtin_amdgcn_fence(__ATOMIC_RELEASE, "agent");
;         asm volatile("s_waitcnt vmcnt(0)" ::: "memory");
;         __hip_atomic_fetch_add(ctr, 1u, __ATOMIC_RELAXED, __HIP_MEMORY_SCOPE_AGENT);
;         while (__hip_atomic_load(ctr, __ATOMIC_RELAXED, __HIP_MEMORY_SCOPE_AGENT) < gen * G) __builtin_amdgcn_s_sleep(32);
;         __builtin_amdgcn_fence(__ATOMIC_ACQUIRE, "agent");
;         asm volatile("s_waitcnt vmcnt(0)" ::: "memory");
;     }
;     __syncthreads();
; }
; __global__ void __launch_bounds__(NTHREADS) fwd_megakernel(Params p) {
;     ...
;     SYNC(12)
.LBB0_3730:
	s_or_b64 exec, exec, s[4:5]
	v_cmp_gt_i32_e32 vcc, 13, v1
	v_cmp_lt_i32_e64 s[2:3], 13, v5
	s_and_b64 s[0:1], vcc, s[2:3]
	s_and_saveexec_b64 s[2:3], s[0:1]
	s_cbranch_execz .LBB0_3739
	s_waitcnt vmcnt(0)
	v_and_b32_e32 v2, 0x3ff, v0
	v_add_u32_e32 v210, 1, v210
	v_cmp_eq_u32_e32 vcc, 0, v2
	s_waitcnt vmcnt(0) lgkmcnt(0)
	s_barrier
	s_and_saveexec_b64 s[4:5], vcc
	s_cbranch_execz .LBB0_3738
	s_getreg_b32 s1, hwreg(HW_REG_XCC_ID, 0, 4)
	s_lshl_b32 s1, s1, 8
	s_add_u32 s12, s42, 0x600000
	s_addc_u32 s13, s43, 0
	s_add_u32 s12, s12, s1
	s_addc_u32 s13, s13, 0
	s_add_u32 s14, s42, 0x601000
	s_addc_u32 s15, s43, 0
	s_lshr_b32 s16, s86, 3
	v_mov_b32_e32 v2, 0
	v_mov_b32_e32 v3, 1
	v_mov_b32_e32 v7, v210
	global_atomic_add v4, v2, v3, s[12:13] sc0
	v_mul_lo_u32 v8, v7, s16
	s_mov_b32 s0, 0
	s_waitcnt vmcnt(0)
	v_add_u32_e32 v4, 1, v4
	v_cmp_eq_u32_e32 vcc, v4, v8
	s_cbranch_vccz .Lxb_nl_11
	buffer_wbl2 sc1
	s_waitcnt vmcnt(0)
	global_atomic_add v4, v2, v3, s[14:15] sc0
	v_lshlrev_b32_e32 v8, 3, v7
	s_waitcnt vmcnt(0)
	v_add_u32_e32 v4, 1, v4
	v_cmp_eq_u32_e32 vcc, v4, v8
	s_cbranch_vccz .Lxb_wt_11
	global_atomic_add v2, v3, s[14:15] offset:256
	s_branch .Lxb_lr_11

; #define SYNC(k) if (p.ph_lo <= (k) && (k) + 1 < p.ph_hi) { if ((k) == 0) grid.sync(); else gbar(bctr, bgen, gridDim.x); }
; DI void gbar(unsigned* ctr, unsigned& gen, unsigned G) {
;     ...
;         asm volatile("s_waitcnt vmcnt(0)" ::: "memory");
;     }
;     __syncthreads();
; __global__ void __launch_bounds__(NTHREADS) fwd_megakernel(Params p) {
;     ...
;     SYNC(12)
.Lxb_na_11:
	buffer_inv sc1
	s_waitcnt vmcnt(0)
.Lxb_dn_11:
	v_mov_b32_e32 v1, s90
	v_mov_b32_e32 v5, s91
.LBB0_3738:
	s_or_b64 exec, exec, s[4:5]
	s_barrier

; #define SYNC(k) if (p.ph_lo <= (k) && (k) + 1 < p.ph_hi) { if ((k) == 0) grid.sync(); else gbar(bctr, bgen, gridDim.x); }
; DI void gbar(unsigned* ctr, unsigned& gen, unsigned G) {
;     asm volatile("s_waitcnt vmcnt(0)" ::: "memory");
;     __syncthreads();
;     gen += 1;
;     if (threadIdx.x == 0) {
;         __builtin_amdgcn_fence(__ATOMIC_RELEASE, "agent");
;         asm volatile("s_waitcnt vmcnt(0)" ::: "memory");
;         __hip_atomic_fetch_add(ctr, 1u, __ATOMIC_RELAXED, __HIP_MEMORY_SCOPE_AGENT);
;         while (__hip_atomic_load(ctr, __ATOMIC_RELAXED, __HIP_MEMORY_SCOPE_AGENT) < gen * G) __builtin_amdgcn_s_sleep(32);
;         __builtin_amdgcn_fence(__ATOMIC_ACQUIRE, "agent");
;         asm volatile("s_waitcnt vmcnt(0)" ::: "memory");
;     }
;     __syncthreads();
; }
; __global__ void __launch_bounds__(NTHREADS) fwd_megakernel(Params p) {
;     ...
;     SYNC(13)
.LBB0_3782:
	s_or_b64 exec, exec, s[6:7]
	v_cmp_gt_i32_e32 vcc, 14, v1
	v_cmp_lt_i32_e64 s[2:3], 14, v5
	s_and_b64 s[0:1], vcc, s[2:3]
	s_and_saveexec_b64 s[2:3], s[0:1]
	s_cbranch_execz .LBB0_3791
	s_waitcnt vmcnt(0)
	v_and_b32_e32 v2, 0x3ff, v0
	v_cmp_eq_u32_e32 vcc, 0, v2
	s_waitcnt vmcnt(0) lgkmcnt(0)
	s_barrier
	s_and_saveexec_b64 s[4:5], vcc
	s_cbranch_execz .LBB0_3790
	s_getreg_b32 s1, hwreg(HW_REG_XCC_ID, 0, 4)
	s_lshl_b32 s1, s1, 8
	s_add_u32 s12, s42, 0x600000
	s_addc_u32 s13, s43, 0
	s_add_u32 s12, s12, s1
	s_addc_u32 s13, s13, 0
	s_add_u32 s14, s42, 0x601000
	s_addc_u32 s15, s43, 0
	s_lshr_b32 s16, s86, 3
	v_mov_b32_e32 v2, 0
	v_mov_b32_e32 v3, 1
	v_add_u32_e32 v7, 1, v210
	global_atomic_add v4, v2, v3, s[12:13] sc0
	v_mul_lo_u32 v8, v7, s16
	s_mov_b32 s0, 0
	s_waitcnt vmcnt(0)
	v_add_u32_e32 v4, 1, v4
	v_cmp_eq_u32_e32 vcc, v4, v8
	s_cbranch_vccz .Lxb_nl_12
	buffer_wbl2 sc1
	s_waitcnt vmcnt(0)
	global_atomic_add v4, v2, v3, s[14:15] sc0
	v_lshlrev_b32_e32 v8, 3, v7
	s_waitcnt vmcnt(0)
	v_add_u32_e32 v4, 1, v4
	v_cmp_eq_u32_e32 vcc, v4, v8
	s_cbranch_vccz .Lxb_wt_12
	global_atomic_add v2, v3, s[14:15] offset:256
	s_branch .Lxb_lr_12

; #define SYNC(k) if (p.ph_lo <= (k) && (k) + 1 < p.ph_hi) { if ((k) == 0) grid.sync(); else gbar(bctr, bgen, gridDim.x); }
; DI void gbar(unsigned* ctr, unsigned& gen, unsigned G) {
;     ...
;         asm volatile("s_waitcnt vmcnt(0)" ::: "memory");
;     }
;     __syncthreads();
; __global__ void __launch_bounds__(NTHREADS) fwd_megakernel(Params p) {
;     ...
;     SYNC(13)
.Lxb_na_12:
	buffer_inv sc1
	s_waitcnt vmcnt(0)
.Lxb_dn_12:
	v_mov_b32_e32 v1, s90
	v_mov_b32_e32 v5, s91
.LBB0_3790:
	s_or_b64 exec, exec, s[4:5]
	s_barrier
